# accumulator zeroing at each GEMM unit start via 63 v_pk_mov_b32 (2 dwords/instr) instead of 126 v_mov_b32, all 8 K-loop pre-headers
# speedup vs baseline: 1.0037x; 1.0037x over previous
;     __host__ __device__ bool unit(int L, Unit& u) const { return order_mn(L, RT / 256, 32, u); }
;     __host__ __device__ const char* a_base(const Unit& u, int) const { return ((u.pn < 16 || u.pm >= 128) ? HX : HXV) + (size_t)u.pm * 256 * 128; }
;     __host__ __device__ bool unit(int L, Unit& u) const { if (L >= NCHB / 256) return false; u.g = g; u.pm = 0; u.pn = b * (NCHB / 256) + L; u.ks = 0; return true; }
;     __host__ __device__ bool unit(int L, Unit& u) const { constexpr int nN = TP / 256, nM = NCHB / 256; if (L >= nN * nM) return false; u.g = g; u.pm = b * nM + L / nN; u.pn = L % nN; u.ks = 0; return true; }
;     __host__ __device__ bool unit(int L, Unit& u) const { return order_mn(L, RL / 256, 8, u); }
;     __host__ __device__ bool unit(int L, Unit& u) const { return order_mn(L, RL / 256, 4, u); }
; template <class P>
; __device__ __forceinline__ void gemm_phase(LAS unsigned char* lds, const P& p, const int G, const int c) {
;     ...
;         const bool has_next = p.unit((ui + 1) * G + c, nxt);
;         const int nt = p.nt(cur);
;         const char* nA0 = has_next ? p.a_base(nxt, 0) - p.a_bias(0) : cA0; const char* nA1 = has_next ? p.a_base(nxt, S1) - p.a_bias(S1) : cA1;
;         const char* nB0 = has_next ? p.b_base(nxt, 0) - p.b_bias(0) : cB0; const char* nB1 = has_next ? p.b_base(nxt, S1) - p.b_bias(S1) : cB1;
;     ...
; #pragma unroll
;         for (int a = 0; a < 2; ++a)
; #pragma unroll
;             for (int b = 0; b < 2; ++b)
; #pragma unroll
;                 for (int m = 0; m < 4; ++m)
; #pragma unroll
;                     for (int n = 0; n < 2; ++n) acc[a][b][m][n] = (f32x4){0.f, 0.f, 0.f, 0.f};
;         cur = nxt; ++ui; cA0 = nA0; cA1 = nA1; cB0 = nB0; cB1 = nB1;
.LBB0_154:
	s_cmp_lt_i32 s88, 16
	s_cselect_b64 s[18:19], -1, 0
	s_cmpk_gt_i32 s68, 0x7f
	s_cselect_b64 s[30:31], -1, 0
	s_ashr_i32 s69, s68, 31
	s_or_b64 s[18:19], s[18:19], s[30:31]
	s_lshl_b64 s[30:31], s[68:69], 15
	v_readlane_b32 s52, v253, 7
	s_and_b64 s[18:19], s[18:19], exec
	v_readlane_b32 s66, v253, 21
	v_readlane_b32 s67, v253, 22
	s_cselect_b32 s19, s3, s66
	s_cselect_b32 s18, s24, s67
	s_add_u32 s72, s19, s30
	s_addc_u32 s73, s18, s31
	s_and_b64 s[18:19], s[70:71], exec
	s_cselect_b32 s18, s73, s83
	s_cselect_b32 s19, s72, s82
	s_ashr_i32 s89, s88, 31
	s_lshl_b64 s[30:31], s[88:89], 15
	s_add_u32 s76, s25, s30
	s_addc_u32 s77, s26, s31
	s_and_b64 s[30:31], s[70:71], exec
	s_cselect_b32 s30, s77, s29
	s_cselect_b32 s31, s76, s28
	s_add_u32 s28, s28, 0x200000
	v_mov_b32_e32 v2, 0
	v_mov_b32_e32 v3, v2
	s_addc_u32 s29, s29, 0
	v_lshl_add_u64 v[54:55], s[82:83], 0, v[148:149]
	s_mov_b32 s52, -2
	s_mov_b64 s[84:85], 0
	v_pk_mov_b32 v[4:5], v[2:3], v[2:3]
	v_pk_mov_b32 v[66:67], v[2:3], v[2:3]
	v_pk_mov_b32 v[68:69], v[2:3], v[2:3]
	v_pk_mov_b32 v[10:11], v[2:3], v[2:3]
	v_pk_mov_b32 v[12:13], v[2:3], v[2:3]
	v_pk_mov_b32 v[82:83], v[2:3], v[2:3]
	v_pk_mov_b32 v[84:85], v[2:3], v[2:3]
	v_pk_mov_b32 v[18:19], v[2:3], v[2:3]
	v_pk_mov_b32 v[20:21], v[2:3], v[2:3]
	v_pk_mov_b32 v[86:87], v[2:3], v[2:3]
	v_pk_mov_b32 v[88:89], v[2:3], v[2:3]
	v_pk_mov_b32 v[26:27], v[2:3], v[2:3]
	v_pk_mov_b32 v[28:29], v[2:3], v[2:3]
	v_pk_mov_b32 v[118:119], v[2:3], v[2:3]
	v_pk_mov_b32 v[120:121], v[2:3], v[2:3]
	v_pk_mov_b32 v[78:79], v[2:3], v[2:3]
	v_pk_mov_b32 v[80:81], v[2:3], v[2:3]
	v_pk_mov_b32 v[6:7], v[2:3], v[2:3]
	v_pk_mov_b32 v[8:9], v[2:3], v[2:3]
	v_pk_mov_b32 v[90:91], v[2:3], v[2:3]
	v_pk_mov_b32 v[92:93], v[2:3], v[2:3]
	v_pk_mov_b32 v[14:15], v[2:3], v[2:3]
	v_pk_mov_b32 v[16:17], v[2:3], v[2:3]
	v_pk_mov_b32 v[94:95], v[2:3], v[2:3]
	v_pk_mov_b32 v[96:97], v[2:3], v[2:3]
	v_pk_mov_b32 v[22:23], v[2:3], v[2:3]
	v_pk_mov_b32 v[24:25], v[2:3], v[2:3]
	v_pk_mov_b32 v[122:123], v[2:3], v[2:3]
	v_pk_mov_b32 v[124:125], v[2:3], v[2:3]
	v_pk_mov_b32 v[30:31], v[2:3], v[2:3]
	v_pk_mov_b32 v[32:33], v[2:3], v[2:3]
	v_pk_mov_b32 v[34:35], v[2:3], v[2:3]
	v_pk_mov_b32 v[36:37], v[2:3], v[2:3]
	v_pk_mov_b32 v[126:127], v[2:3], v[2:3]
	v_pk_mov_b32 v[128:129], v[2:3], v[2:3]
	v_pk_mov_b32 v[42:43], v[2:3], v[2:3]
	v_pk_mov_b32 v[44:45], v[2:3], v[2:3]
	v_pk_mov_b32 v[102:103], v[2:3], v[2:3]
	v_pk_mov_b32 v[104:105], v[2:3], v[2:3]
	v_pk_mov_b32 v[50:51], v[2:3], v[2:3]
	v_pk_mov_b32 v[52:53], v[2:3], v[2:3]
	v_pk_mov_b32 v[106:107], v[2:3], v[2:3]
	v_pk_mov_b32 v[108:109], v[2:3], v[2:3]
	v_pk_mov_b32 v[74:75], v[2:3], v[2:3]
	v_pk_mov_b32 v[76:77], v[2:3], v[2:3]
	v_pk_mov_b32 v[134:135], v[2:3], v[2:3]
	v_pk_mov_b32 v[136:137], v[2:3], v[2:3]
	v_pk_mov_b32 v[130:131], v[2:3], v[2:3]
	v_pk_mov_b32 v[132:133], v[2:3], v[2:3]
	v_pk_mov_b32 v[38:39], v[2:3], v[2:3]
	v_pk_mov_b32 v[40:41], v[2:3], v[2:3]
	v_pk_mov_b32 v[110:111], v[2:3], v[2:3]
	v_pk_mov_b32 v[112:113], v[2:3], v[2:3]
	v_pk_mov_b32 v[46:47], v[2:3], v[2:3]
	v_pk_mov_b32 v[48:49], v[2:3], v[2:3]
	v_pk_mov_b32 v[114:115], v[2:3], v[2:3]
	v_pk_mov_b32 v[116:117], v[2:3], v[2:3]
	v_pk_mov_b32 v[70:71], v[2:3], v[2:3]
	v_pk_mov_b32 v[72:73], v[2:3], v[2:3]
	v_pk_mov_b32 v[138:139], v[2:3], v[2:3]
	v_pk_mov_b32 v[140:141], v[2:3], v[2:3]
	v_pk_mov_b32 v[98:99], v[2:3], v[2:3]
	v_pk_mov_b32 v[100:101], v[2:3], v[2:3]
	v_readlane_b32 s53, v253, 8
	v_readlane_b32 s54, v253, 9
	v_readlane_b32 s55, v253, 10
	v_readlane_b32 s56, v253, 11
	v_readlane_b32 s57, v253, 12
	v_readlane_b32 s58, v253, 13
	v_readlane_b32 s59, v253, 14
	v_readlane_b32 s60, v253, 15
	v_readlane_b32 s61, v253, 16
	v_readlane_b32 s62, v253, 17
	v_readlane_b32 s63, v253, 18
	v_readlane_b32 s64, v253, 19
	v_readlane_b32 s65, v253, 20

;     __host__ __device__ bool unit(int L, Unit& u) const { return order_mn(L, RT / 256, 32, u); }
;     __host__ __device__ const char* a_base(const Unit& u, int) const { return ((u.pn < 16 || u.pm >= 128) ? HX : HXV) + (size_t)u.pm * 256 * 128; }
;     __host__ __device__ bool unit(int L, Unit& u) const { if (L >= NCHB / 256) return false; u.g = g; u.pm = 0; u.pn = b * (NCHB / 256) + L; u.ks = 0; return true; }
;     __host__ __device__ bool unit(int L, Unit& u) const { constexpr int nN = TP / 256, nM = NCHB / 256; if (L >= nN * nM) return false; u.g = g; u.pm = b * nM + L / nN; u.pn = L % nN; u.ks = 0; return true; }
;     __host__ __device__ bool unit(int L, Unit& u) const { return order_mn(L, RL / 256, 8, u); }
;     __host__ __device__ bool unit(int L, Unit& u) const { return order_mn(L, RL / 256, 4, u); }
; template <class P>
; __device__ __forceinline__ void gemm_phase(LAS unsigned char* lds, const P& p, const int G, const int c) {
;     ...
;         const bool has_next = p.unit((ui + 1) * G + c, nxt);
;         const int nt = p.nt(cur);
;         const char* nA0 = has_next ? p.a_base(nxt, 0) - p.a_bias(0) : cA0; const char* nA1 = has_next ? p.a_base(nxt, S1) - p.a_bias(S1) : cA1;
;         const char* nB0 = has_next ? p.b_base(nxt, 0) - p.b_bias(0) : cB0; const char* nB1 = has_next ? p.b_base(nxt, S1) - p.b_bias(S1) : cB1;
;     ...
; #pragma unroll
;         for (int a = 0; a < 2; ++a)
; #pragma unroll
;             for (int b = 0; b < 2; ++b)
; #pragma unroll
;                 for (int m = 0; m < 4; ++m)
; #pragma unroll
;                     for (int n = 0; n < 2; ++n) acc[a][b][m][n] = (f32x4){0.f, 0.f, 0.f, 0.f};
;         cur = nxt; ++ui; cA0 = nA0; cA1 = nA1; cB0 = nB0; cB1 = nB1;
.LBB0_276:
	s_cmpk_lt_i32 s8, 0x80
	s_cselect_b64 s[74:75], -1, 0
	s_cmpk_gt_i32 s8, 0x7f
	s_cselect_b32 s5, 4, 32
	s_ashr_i32 s61, s60, 31
	s_lshl_b64 s[18:19], s[60:61], 15
	s_lshl_b64 s[28:29], s[54:55], 19
	s_add_u32 s7, s24, s18
	s_addc_u32 s18, s25, s19
	s_add_u32 s82, s7, s28
	s_addc_u32 s83, s18, s29
	s_and_b64 s[18:19], exec, s[62:63]
	s_cselect_b32 s7, s83, s77
	s_cselect_b32 s18, s82, s76
	s_add_u32 s19, s76, 0x40000
	s_mul_i32 s28, s5, 0x410000
	v_mov_b32_e32 v2, 0
	v_mov_b32_e32 v3, v2
	s_addc_u32 s49, s77, 0
	v_lshl_add_u64 v[130:131], s[72:73], 0, v[172:173]
	s_add_i32 s55, s28, 0xff7e0000
	s_mov_b32 s57, 0
	s_mov_b64 s[76:77], 0
	v_pk_mov_b32 v[4:5], v[2:3], v[2:3]
	v_pk_mov_b32 v[6:7], v[2:3], v[2:3]
	v_pk_mov_b32 v[8:9], v[2:3], v[2:3]
	v_pk_mov_b32 v[10:11], v[2:3], v[2:3]
	v_pk_mov_b32 v[12:13], v[2:3], v[2:3]
	v_pk_mov_b32 v[14:15], v[2:3], v[2:3]
	v_pk_mov_b32 v[16:17], v[2:3], v[2:3]
	v_pk_mov_b32 v[18:19], v[2:3], v[2:3]
	v_pk_mov_b32 v[20:21], v[2:3], v[2:3]
	v_pk_mov_b32 v[26:27], v[2:3], v[2:3]
	v_pk_mov_b32 v[28:29], v[2:3], v[2:3]
	v_pk_mov_b32 v[34:35], v[2:3], v[2:3]
	v_pk_mov_b32 v[36:37], v[2:3], v[2:3]
	v_pk_mov_b32 v[42:43], v[2:3], v[2:3]
	v_pk_mov_b32 v[44:45], v[2:3], v[2:3]
	v_pk_mov_b32 v[22:23], v[2:3], v[2:3]
	v_pk_mov_b32 v[24:25], v[2:3], v[2:3]
	v_pk_mov_b32 v[30:31], v[2:3], v[2:3]
	v_pk_mov_b32 v[32:33], v[2:3], v[2:3]
	v_pk_mov_b32 v[38:39], v[2:3], v[2:3]
	v_pk_mov_b32 v[40:41], v[2:3], v[2:3]
	v_pk_mov_b32 v[46:47], v[2:3], v[2:3]
	v_pk_mov_b32 v[48:49], v[2:3], v[2:3]
	v_pk_mov_b32 v[50:51], v[2:3], v[2:3]
	v_pk_mov_b32 v[52:53], v[2:3], v[2:3]
	v_pk_mov_b32 v[54:55], v[2:3], v[2:3]
	v_pk_mov_b32 v[56:57], v[2:3], v[2:3]
	v_pk_mov_b32 v[58:59], v[2:3], v[2:3]
	v_pk_mov_b32 v[60:61], v[2:3], v[2:3]
	v_pk_mov_b32 v[62:63], v[2:3], v[2:3]
	v_pk_mov_b32 v[64:65], v[2:3], v[2:3]
	v_pk_mov_b32 v[66:67], v[2:3], v[2:3]
	v_pk_mov_b32 v[68:69], v[2:3], v[2:3]
	v_pk_mov_b32 v[70:71], v[2:3], v[2:3]
	v_pk_mov_b32 v[72:73], v[2:3], v[2:3]
	v_pk_mov_b32 v[74:75], v[2:3], v[2:3]
	v_pk_mov_b32 v[76:77], v[2:3], v[2:3]
	v_pk_mov_b32 v[78:79], v[2:3], v[2:3]
	v_pk_mov_b32 v[80:81], v[2:3], v[2:3]
	v_pk_mov_b32 v[82:83], v[2:3], v[2:3]
	v_pk_mov_b32 v[84:85], v[2:3], v[2:3]
	v_pk_mov_b32 v[90:91], v[2:3], v[2:3]
	v_pk_mov_b32 v[92:93], v[2:3], v[2:3]
	v_pk_mov_b32 v[102:103], v[2:3], v[2:3]
	v_pk_mov_b32 v[104:105], v[2:3], v[2:3]
	v_pk_mov_b32 v[110:111], v[2:3], v[2:3]
	v_pk_mov_b32 v[112:113], v[2:3], v[2:3]
	v_pk_mov_b32 v[86:87], v[2:3], v[2:3]
	v_pk_mov_b32 v[88:89], v[2:3], v[2:3]
	v_pk_mov_b32 v[94:95], v[2:3], v[2:3]
	v_pk_mov_b32 v[96:97], v[2:3], v[2:3]
	v_pk_mov_b32 v[98:99], v[2:3], v[2:3]
	v_pk_mov_b32 v[100:101], v[2:3], v[2:3]
	v_pk_mov_b32 v[106:107], v[2:3], v[2:3]
	v_pk_mov_b32 v[108:109], v[2:3], v[2:3]
	v_pk_mov_b32 v[114:115], v[2:3], v[2:3]
	v_pk_mov_b32 v[116:117], v[2:3], v[2:3]
	v_pk_mov_b32 v[118:119], v[2:3], v[2:3]
	v_pk_mov_b32 v[120:121], v[2:3], v[2:3]
	v_pk_mov_b32 v[122:123], v[2:3], v[2:3]
	v_pk_mov_b32 v[124:125], v[2:3], v[2:3]
	v_pk_mov_b32 v[126:127], v[2:3], v[2:3]
	v_pk_mov_b32 v[128:129], v[2:3], v[2:3]
	s_branch .LBB0_278

;     __host__ __device__ bool unit(int L, Unit& u) const { return order_mn(L, RT / 256, 32, u); }
;     __host__ __device__ const char* a_base(const Unit& u, int) const { return ((u.pn < 16 || u.pm >= 128) ? HX : HXV) + (size_t)u.pm * 256 * 128; }
;     __host__ __device__ bool unit(int L, Unit& u) const { if (L >= NCHB / 256) return false; u.g = g; u.pm = 0; u.pn = b * (NCHB / 256) + L; u.ks = 0; return true; }
;     __host__ __device__ bool unit(int L, Unit& u) const { constexpr int nN = TP / 256, nM = NCHB / 256; if (L >= nN * nM) return false; u.g = g; u.pm = b * nM + L / nN; u.pn = L % nN; u.ks = 0; return true; }
;     __host__ __device__ bool unit(int L, Unit& u) const { return order_mn(L, RL / 256, 8, u); }
;     __host__ __device__ bool unit(int L, Unit& u) const { return order_mn(L, RL / 256, 4, u); }
; template <class P>
; __device__ __forceinline__ void gemm_phase(LAS unsigned char* lds, const P& p, const int G, const int c) {
;     ...
;         const bool has_next = p.unit((ui + 1) * G + c, nxt);
;         const int nt = p.nt(cur);
;         const char* nA0 = has_next ? p.a_base(nxt, 0) - p.a_bias(0) : cA0; const char* nA1 = has_next ? p.a_base(nxt, S1) - p.a_bias(S1) : cA1;
;         const char* nB0 = has_next ? p.b_base(nxt, 0) - p.b_bias(0) : cB0; const char* nB1 = has_next ? p.b_base(nxt, S1) - p.b_bias(S1) : cB1;
;     ...
; #pragma unroll
;         for (int a = 0; a < 2; ++a)
; #pragma unroll
;             for (int b = 0; b < 2; ++b)
; #pragma unroll
;                 for (int m = 0; m < 4; ++m)
; #pragma unroll
;                     for (int n = 0; n < 2; ++n) acc[a][b][m][n] = (f32x4){0.f, 0.f, 0.f, 0.f};
;         cur = nxt; ++ui; cA0 = nA0; cA1 = nA1; cB0 = nB0; cB1 = nB1;
.LBB0_409:
	s_cmpk_lt_i32 s0, 0x80
	s_cselect_b64 s[68:69], -1, 0
	s_cmpk_gt_i32 s0, 0x7f
	s_cselect_b32 s1, 4, 16
	s_lshl_b32 s18, s72, 8
	s_ashr_i32 s19, s18, 31
	s_lshl_b64 s[18:19], s[18:19], 7
	s_lshl_b64 s[28:29], s[52:53], 21
	s_add_u32 s7, s24, s18
	s_addc_u32 s18, s25, s19
	s_add_u32 s60, s7, s28
	s_addc_u32 s61, s18, s29
	s_and_b64 s[18:19], exec, s[56:57]
	s_cselect_b32 s7, s61, s71
	s_cselect_b32 s18, s60, s70
	s_add_u32 s19, s70, 0x100000
	s_mul_i32 s28, s1, 0x410000
	v_mov_b32_e32 v2, 0
	v_mov_b32_e32 v3, v2
	s_addc_u32 s53, s71, 0
	v_lshl_add_u64 v[140:141], s[62:63], 0, v[138:139]
	s_add_i32 s55, s28, 0xff7e0000
	s_mov_b32 s74, 0
	s_mov_b64 s[70:71], 0
	v_pk_mov_b32 v[4:5], v[2:3], v[2:3]
	v_pk_mov_b32 v[6:7], v[2:3], v[2:3]
	v_pk_mov_b32 v[8:9], v[2:3], v[2:3]
	v_pk_mov_b32 v[18:19], v[2:3], v[2:3]
	v_pk_mov_b32 v[20:21], v[2:3], v[2:3]
	v_pk_mov_b32 v[22:23], v[2:3], v[2:3]
	v_pk_mov_b32 v[24:25], v[2:3], v[2:3]
	v_pk_mov_b32 v[34:35], v[2:3], v[2:3]
	v_pk_mov_b32 v[36:37], v[2:3], v[2:3]
	v_pk_mov_b32 v[38:39], v[2:3], v[2:3]
	v_pk_mov_b32 v[40:41], v[2:3], v[2:3]
	v_pk_mov_b32 v[50:51], v[2:3], v[2:3]
	v_pk_mov_b32 v[52:53], v[2:3], v[2:3]
	v_pk_mov_b32 v[54:55], v[2:3], v[2:3]
	v_pk_mov_b32 v[56:57], v[2:3], v[2:3]
	v_pk_mov_b32 v[10:11], v[2:3], v[2:3]
	v_pk_mov_b32 v[12:13], v[2:3], v[2:3]
	v_pk_mov_b32 v[14:15], v[2:3], v[2:3]
	v_pk_mov_b32 v[16:17], v[2:3], v[2:3]
	v_pk_mov_b32 v[26:27], v[2:3], v[2:3]
	v_pk_mov_b32 v[28:29], v[2:3], v[2:3]
	v_pk_mov_b32 v[30:31], v[2:3], v[2:3]
	v_pk_mov_b32 v[32:33], v[2:3], v[2:3]
	v_pk_mov_b32 v[42:43], v[2:3], v[2:3]
	v_pk_mov_b32 v[44:45], v[2:3], v[2:3]
	v_pk_mov_b32 v[46:47], v[2:3], v[2:3]
	v_pk_mov_b32 v[48:49], v[2:3], v[2:3]
	v_pk_mov_b32 v[58:59], v[2:3], v[2:3]
	v_pk_mov_b32 v[60:61], v[2:3], v[2:3]
	v_pk_mov_b32 v[62:63], v[2:3], v[2:3]
	v_pk_mov_b32 v[64:65], v[2:3], v[2:3]
	v_pk_mov_b32 v[66:67], v[2:3], v[2:3]
	v_pk_mov_b32 v[68:69], v[2:3], v[2:3]
	v_pk_mov_b32 v[70:71], v[2:3], v[2:3]
	v_pk_mov_b32 v[72:73], v[2:3], v[2:3]
	v_pk_mov_b32 v[82:83], v[2:3], v[2:3]
	v_pk_mov_b32 v[84:85], v[2:3], v[2:3]
	v_pk_mov_b32 v[86:87], v[2:3], v[2:3]
	v_pk_mov_b32 v[88:89], v[2:3], v[2:3]
	v_pk_mov_b32 v[98:99], v[2:3], v[2:3]
	v_pk_mov_b32 v[100:101], v[2:3], v[2:3]
	v_pk_mov_b32 v[102:103], v[2:3], v[2:3]
	v_pk_mov_b32 v[104:105], v[2:3], v[2:3]
	v_pk_mov_b32 v[114:115], v[2:3], v[2:3]
	v_pk_mov_b32 v[116:117], v[2:3], v[2:3]
	v_pk_mov_b32 v[118:119], v[2:3], v[2:3]
	v_pk_mov_b32 v[120:121], v[2:3], v[2:3]
	v_pk_mov_b32 v[74:75], v[2:3], v[2:3]
	v_pk_mov_b32 v[76:77], v[2:3], v[2:3]
	v_pk_mov_b32 v[78:79], v[2:3], v[2:3]
	v_pk_mov_b32 v[80:81], v[2:3], v[2:3]
	v_pk_mov_b32 v[90:91], v[2:3], v[2:3]
	v_pk_mov_b32 v[92:93], v[2:3], v[2:3]
	v_pk_mov_b32 v[94:95], v[2:3], v[2:3]
	v_pk_mov_b32 v[96:97], v[2:3], v[2:3]
	v_pk_mov_b32 v[106:107], v[2:3], v[2:3]
	v_pk_mov_b32 v[108:109], v[2:3], v[2:3]
	v_pk_mov_b32 v[110:111], v[2:3], v[2:3]
	v_pk_mov_b32 v[112:113], v[2:3], v[2:3]
	v_pk_mov_b32 v[122:123], v[2:3], v[2:3]
	v_pk_mov_b32 v[124:125], v[2:3], v[2:3]
	v_pk_mov_b32 v[126:127], v[2:3], v[2:3]
	v_pk_mov_b32 v[128:129], v[2:3], v[2:3]
	s_branch .LBB0_411

;     __host__ __device__ bool unit(int L, Unit& u) const { return order_mn(L, RT / 256, 32, u); }
;     __host__ __device__ const char* a_base(const Unit& u, int) const { return ((u.pn < 16 || u.pm >= 128) ? HX : HXV) + (size_t)u.pm * 256 * 128; }
;     __host__ __device__ bool unit(int L, Unit& u) const { if (L >= NCHB / 256) return false; u.g = g; u.pm = 0; u.pn = b * (NCHB / 256) + L; u.ks = 0; return true; }
;     __host__ __device__ bool unit(int L, Unit& u) const { constexpr int nN = TP / 256, nM = NCHB / 256; if (L >= nN * nM) return false; u.g = g; u.pm = b * nM + L / nN; u.pn = L % nN; u.ks = 0; return true; }
;     __host__ __device__ bool unit(int L, Unit& u) const { return order_mn(L, RL / 256, 8, u); }
;     __host__ __device__ bool unit(int L, Unit& u) const { return order_mn(L, RL / 256, 4, u); }
; template <class P>
; __device__ __forceinline__ void gemm_phase(LAS unsigned char* lds, const P& p, const int G, const int c) {
;     ...
;         const bool has_next = p.unit((ui + 1) * G + c, nxt);
;         const int nt = p.nt(cur);
;         const char* nA0 = has_next ? p.a_base(nxt, 0) - p.a_bias(0) : cA0; const char* nA1 = has_next ? p.a_base(nxt, S1) - p.a_bias(S1) : cA1;
;         const char* nB0 = has_next ? p.b_base(nxt, 0) - p.b_bias(0) : cB0; const char* nB1 = has_next ? p.b_base(nxt, S1) - p.b_bias(S1) : cB1;
;     ...
; #pragma unroll
;         for (int a = 0; a < 2; ++a)
; #pragma unroll
;             for (int b = 0; b < 2; ++b)
; #pragma unroll
;                 for (int m = 0; m < 4; ++m)
; #pragma unroll
;                     for (int n = 0; n < 2; ++n) acc[a][b][m][n] = (f32x4){0.f, 0.f, 0.f, 0.f};
;         cur = nxt; ++ui; cA0 = nA0; cA1 = nA1; cB0 = nB0; cB1 = nB1;
.LBB0_538:
	s_lshl_b64 s[18:19], s[18:19], 20
	s_add_u32 s90, s26, s18
	s_addc_u32 s91, s27, s19
	s_and_b64 s[6:7], s[6:7], exec
	s_cselect_b32 s18, s91, s93
	s_cselect_b32 s19, s90, s92
	s_add_u32 s28, s28, 0x40000
	v_mov_b32_e32 v2, 0
	v_mov_b32_e32 v3, v2
	s_addc_u32 s29, s29, 0
	v_lshl_add_u64 v[154:155], s[92:93], 0, v[152:153]
	s_mov_b32 s47, -2
	s_mov_b64 s[94:95], 0
	v_pk_mov_b32 v[4:5], v[2:3], v[2:3]
	v_pk_mov_b32 v[6:7], v[2:3], v[2:3]
	v_pk_mov_b32 v[8:9], v[2:3], v[2:3]
	v_pk_mov_b32 v[10:11], v[2:3], v[2:3]
	v_pk_mov_b32 v[12:13], v[2:3], v[2:3]
	v_pk_mov_b32 v[14:15], v[2:3], v[2:3]
	v_pk_mov_b32 v[16:17], v[2:3], v[2:3]
	v_pk_mov_b32 v[26:27], v[2:3], v[2:3]
	v_pk_mov_b32 v[28:29], v[2:3], v[2:3]
	v_pk_mov_b32 v[30:31], v[2:3], v[2:3]
	v_pk_mov_b32 v[32:33], v[2:3], v[2:3]
	v_pk_mov_b32 v[42:43], v[2:3], v[2:3]
	v_pk_mov_b32 v[44:45], v[2:3], v[2:3]
	v_pk_mov_b32 v[46:47], v[2:3], v[2:3]
	v_pk_mov_b32 v[48:49], v[2:3], v[2:3]
	v_pk_mov_b32 v[18:19], v[2:3], v[2:3]
	v_pk_mov_b32 v[20:21], v[2:3], v[2:3]
	v_pk_mov_b32 v[22:23], v[2:3], v[2:3]
	v_pk_mov_b32 v[24:25], v[2:3], v[2:3]
	v_pk_mov_b32 v[34:35], v[2:3], v[2:3]
	v_pk_mov_b32 v[36:37], v[2:3], v[2:3]
	v_pk_mov_b32 v[38:39], v[2:3], v[2:3]
	v_pk_mov_b32 v[40:41], v[2:3], v[2:3]
	v_pk_mov_b32 v[50:51], v[2:3], v[2:3]
	v_pk_mov_b32 v[52:53], v[2:3], v[2:3]
	v_pk_mov_b32 v[54:55], v[2:3], v[2:3]
	v_pk_mov_b32 v[56:57], v[2:3], v[2:3]
	v_pk_mov_b32 v[58:59], v[2:3], v[2:3]
	v_pk_mov_b32 v[60:61], v[2:3], v[2:3]
	v_pk_mov_b32 v[62:63], v[2:3], v[2:3]
	v_pk_mov_b32 v[64:65], v[2:3], v[2:3]
	v_pk_mov_b32 v[66:67], v[2:3], v[2:3]
	v_pk_mov_b32 v[68:69], v[2:3], v[2:3]
	v_pk_mov_b32 v[70:71], v[2:3], v[2:3]
	v_pk_mov_b32 v[72:73], v[2:3], v[2:3]
	v_pk_mov_b32 v[74:75], v[2:3], v[2:3]
	v_pk_mov_b32 v[76:77], v[2:3], v[2:3]
	v_pk_mov_b32 v[78:79], v[2:3], v[2:3]
	v_pk_mov_b32 v[80:81], v[2:3], v[2:3]
	v_pk_mov_b32 v[90:91], v[2:3], v[2:3]
	v_pk_mov_b32 v[92:93], v[2:3], v[2:3]
	v_pk_mov_b32 v[94:95], v[2:3], v[2:3]
	v_pk_mov_b32 v[96:97], v[2:3], v[2:3]
	v_pk_mov_b32 v[106:107], v[2:3], v[2:3]
	v_pk_mov_b32 v[108:109], v[2:3], v[2:3]
	v_pk_mov_b32 v[110:111], v[2:3], v[2:3]
	v_pk_mov_b32 v[112:113], v[2:3], v[2:3]
	v_pk_mov_b32 v[82:83], v[2:3], v[2:3]
	v_pk_mov_b32 v[84:85], v[2:3], v[2:3]
	v_pk_mov_b32 v[86:87], v[2:3], v[2:3]
	v_pk_mov_b32 v[88:89], v[2:3], v[2:3]
	v_pk_mov_b32 v[98:99], v[2:3], v[2:3]
	v_pk_mov_b32 v[100:101], v[2:3], v[2:3]
	v_pk_mov_b32 v[102:103], v[2:3], v[2:3]
	v_pk_mov_b32 v[104:105], v[2:3], v[2:3]
	v_pk_mov_b32 v[114:115], v[2:3], v[2:3]
	v_pk_mov_b32 v[116:117], v[2:3], v[2:3]
	v_pk_mov_b32 v[118:119], v[2:3], v[2:3]
	v_pk_mov_b32 v[120:121], v[2:3], v[2:3]
	v_pk_mov_b32 v[122:123], v[2:3], v[2:3]
	v_pk_mov_b32 v[124:125], v[2:3], v[2:3]
	v_pk_mov_b32 v[126:127], v[2:3], v[2:3]
	v_pk_mov_b32 v[128:129], v[2:3], v[2:3]

;     __host__ __device__ bool unit(int L, Unit& u) const { return order_mn(L, RT / 256, 32, u); }
;     __host__ __device__ const char* a_base(const Unit& u, int) const { return ((u.pn < 16 || u.pm >= 128) ? HX : HXV) + (size_t)u.pm * 256 * 128; }
;     __host__ __device__ bool unit(int L, Unit& u) const { if (L >= NCHB / 256) return false; u.g = g; u.pm = 0; u.pn = b * (NCHB / 256) + L; u.ks = 0; return true; }
;     __host__ __device__ bool unit(int L, Unit& u) const { constexpr int nN = TP / 256, nM = NCHB / 256; if (L >= nN * nM) return false; u.g = g; u.pm = b * nM + L / nN; u.pn = L % nN; u.ks = 0; return true; }
;     __host__ __device__ bool unit(int L, Unit& u) const { return order_mn(L, RL / 256, 8, u); }
;     __host__ __device__ bool unit(int L, Unit& u) const { return order_mn(L, RL / 256, 4, u); }
; template <class P>
; __device__ __forceinline__ void gemm_phase(LAS unsigned char* lds, const P& p, const int G, const int c) {
;     ...
;         const bool has_next = p.unit((ui + 1) * G + c, nxt);
;         const int nt = p.nt(cur);
;         const char* nA0 = has_next ? p.a_base(nxt, 0) - p.a_bias(0) : cA0; const char* nA1 = has_next ? p.a_base(nxt, S1) - p.a_bias(S1) : cA1;
;         const char* nB0 = has_next ? p.b_base(nxt, 0) - p.b_bias(0) : cB0; const char* nB1 = has_next ? p.b_base(nxt, S1) - p.b_bias(S1) : cB1;
;     ...
; #pragma unroll
;         for (int a = 0; a < 2; ++a)
; #pragma unroll
;             for (int b = 0; b < 2; ++b)
; #pragma unroll
;                 for (int m = 0; m < 4; ++m)
; #pragma unroll
;                     for (int n = 0; n < 2; ++n) acc[a][b][m][n] = (f32x4){0.f, 0.f, 0.f, 0.f};
;         cur = nxt; ++ui; cA0 = nA0; cA1 = nA1; cB0 = nB0; cB1 = nB1;
.LBB0_582:
	s_mov_b32 s55, s54
	s_add_i32 s54, s54, 1
	s_cmp_lt_u32 s55, 3
	s_cselect_b64 s[80:81], -1, 0
	s_lshr_b32 s6, s54, 1
	s_add_i32 s82, s6, s67
	s_and_b32 s16, s54, 1
	s_and_b64 s[6:7], s[80:81], exec
	s_mov_b32 s83, s17
	s_mov_b32 s73, s72
	s_cselect_b32 s72, s16, s72
	s_lshl_b64 s[6:7], s[82:83], 15
	s_add_u32 s16, s62, s6
	s_addc_u32 s18, s63, s7
	s_mov_b64 s[86:87], s[30:31]
	s_and_b64 s[6:7], s[80:81], exec
	s_cselect_b32 s31, s18, s87
	s_cselect_b32 s30, s16, s86
	s_ashr_i32 s16, s78, 31
	s_and_b64 s[6:7], s[80:81], exec
	s_cselect_b32 s85, s61, s16
	s_cselect_b32 s84, s60, s78
	s_lshl_b32 s16, s72, 4
	s_sub_i32 s18, 31, s16
	s_ashr_i32 s19, s18, 31
	s_lshl_b64 s[6:7], s[84:85], 15
	s_lshl_b64 s[18:19], s[18:19], 5
	s_add_u32 s6, s0, s6
	s_addc_u32 s7, s1, s7
	s_add_u32 s6, s6, s18
	s_addc_u32 s7, s7, s19
	s_add_u32 s16, s6, 0xffffffa0
	s_addc_u32 s18, s7, -1
	s_mov_b64 s[88:89], s[76:77]
	s_and_b64 s[6:7], s[80:81], exec
	s_cselect_b32 s77, s18, s89
	s_cselect_b32 s76, s16, s88
	s_add_u32 s90, s15, 0xfffa0000
	s_addc_u32 s91, s46, -1
	s_add_u32 s92, s2, 0xfff40000
	s_addc_u32 s93, s14, -1
	s_add_u32 s94, s86, 0x20000
	v_mov_b32_e32 v2, 0
	v_mov_b32_e32 v3, v2
	s_addc_u32 s95, s87, 0
	s_mov_b32 s18, -2
	s_mov_b32 s79, 0
	s_mov_b32 s83, 0
	v_pk_mov_b32 v[4:5], v[2:3], v[2:3]
	v_pk_mov_b32 v[6:7], v[2:3], v[2:3]
	v_pk_mov_b32 v[8:9], v[2:3], v[2:3]
	v_pk_mov_b32 v[18:19], v[2:3], v[2:3]
	v_pk_mov_b32 v[20:21], v[2:3], v[2:3]
	v_pk_mov_b32 v[22:23], v[2:3], v[2:3]
	v_pk_mov_b32 v[24:25], v[2:3], v[2:3]
	v_pk_mov_b32 v[34:35], v[2:3], v[2:3]
	v_pk_mov_b32 v[36:37], v[2:3], v[2:3]
	v_pk_mov_b32 v[38:39], v[2:3], v[2:3]
	v_pk_mov_b32 v[40:41], v[2:3], v[2:3]
	v_pk_mov_b32 v[50:51], v[2:3], v[2:3]
	v_pk_mov_b32 v[52:53], v[2:3], v[2:3]
	v_pk_mov_b32 v[54:55], v[2:3], v[2:3]
	v_pk_mov_b32 v[56:57], v[2:3], v[2:3]
	v_pk_mov_b32 v[10:11], v[2:3], v[2:3]
	v_pk_mov_b32 v[12:13], v[2:3], v[2:3]
	v_pk_mov_b32 v[14:15], v[2:3], v[2:3]
	v_pk_mov_b32 v[16:17], v[2:3], v[2:3]
	v_pk_mov_b32 v[26:27], v[2:3], v[2:3]
	v_pk_mov_b32 v[28:29], v[2:3], v[2:3]
	v_pk_mov_b32 v[30:31], v[2:3], v[2:3]
	v_pk_mov_b32 v[32:33], v[2:3], v[2:3]
	v_pk_mov_b32 v[42:43], v[2:3], v[2:3]
	v_pk_mov_b32 v[44:45], v[2:3], v[2:3]
	v_pk_mov_b32 v[46:47], v[2:3], v[2:3]
	v_pk_mov_b32 v[48:49], v[2:3], v[2:3]
	v_pk_mov_b32 v[58:59], v[2:3], v[2:3]
	v_pk_mov_b32 v[60:61], v[2:3], v[2:3]
	v_pk_mov_b32 v[62:63], v[2:3], v[2:3]
	v_pk_mov_b32 v[64:65], v[2:3], v[2:3]
	v_pk_mov_b32 v[66:67], v[2:3], v[2:3]
	v_pk_mov_b32 v[68:69], v[2:3], v[2:3]
	v_pk_mov_b32 v[70:71], v[2:3], v[2:3]
	v_pk_mov_b32 v[72:73], v[2:3], v[2:3]
	v_pk_mov_b32 v[82:83], v[2:3], v[2:3]
	v_pk_mov_b32 v[84:85], v[2:3], v[2:3]
	v_pk_mov_b32 v[86:87], v[2:3], v[2:3]
	v_pk_mov_b32 v[88:89], v[2:3], v[2:3]
	v_pk_mov_b32 v[98:99], v[2:3], v[2:3]
	v_pk_mov_b32 v[100:101], v[2:3], v[2:3]
	v_pk_mov_b32 v[102:103], v[2:3], v[2:3]
	v_pk_mov_b32 v[104:105], v[2:3], v[2:3]
	v_pk_mov_b32 v[114:115], v[2:3], v[2:3]
	v_pk_mov_b32 v[116:117], v[2:3], v[2:3]
	v_pk_mov_b32 v[118:119], v[2:3], v[2:3]
	v_pk_mov_b32 v[120:121], v[2:3], v[2:3]
	v_pk_mov_b32 v[74:75], v[2:3], v[2:3]
	v_pk_mov_b32 v[76:77], v[2:3], v[2:3]
	v_pk_mov_b32 v[78:79], v[2:3], v[2:3]
	v_pk_mov_b32 v[80:81], v[2:3], v[2:3]
	v_pk_mov_b32 v[90:91], v[2:3], v[2:3]
	v_pk_mov_b32 v[92:93], v[2:3], v[2:3]
	v_pk_mov_b32 v[94:95], v[2:3], v[2:3]
	v_pk_mov_b32 v[96:97], v[2:3], v[2:3]
	v_pk_mov_b32 v[106:107], v[2:3], v[2:3]
	v_pk_mov_b32 v[108:109], v[2:3], v[2:3]
	v_pk_mov_b32 v[110:111], v[2:3], v[2:3]
	v_pk_mov_b32 v[112:113], v[2:3], v[2:3]
	v_pk_mov_b32 v[122:123], v[2:3], v[2:3]
	v_pk_mov_b32 v[124:125], v[2:3], v[2:3]
	v_pk_mov_b32 v[126:127], v[2:3], v[2:3]
	v_pk_mov_b32 v[128:129], v[2:3], v[2:3]
	s_branch .LBB0_584

;     __host__ __device__ bool unit(int L, Unit& u) const { return order_mn(L, RT / 256, 32, u); }
;     __host__ __device__ const char* a_base(const Unit& u, int) const { return ((u.pn < 16 || u.pm >= 128) ? HX : HXV) + (size_t)u.pm * 256 * 128; }
;     __host__ __device__ bool unit(int L, Unit& u) const { if (L >= NCHB / 256) return false; u.g = g; u.pm = 0; u.pn = b * (NCHB / 256) + L; u.ks = 0; return true; }
;     __host__ __device__ bool unit(int L, Unit& u) const { constexpr int nN = TP / 256, nM = NCHB / 256; if (L >= nN * nM) return false; u.g = g; u.pm = b * nM + L / nN; u.pn = L % nN; u.ks = 0; return true; }
;     __host__ __device__ bool unit(int L, Unit& u) const { return order_mn(L, RL / 256, 8, u); }
;     __host__ __device__ bool unit(int L, Unit& u) const { return order_mn(L, RL / 256, 4, u); }
; template <class P>
; __device__ __forceinline__ void gemm_phase(LAS unsigned char* lds, const P& p, const int G, const int c) {
;     ...
;         const bool has_next = p.unit((ui + 1) * G + c, nxt);
;         const int nt = p.nt(cur);
;         const char* nA0 = has_next ? p.a_base(nxt, 0) - p.a_bias(0) : cA0; const char* nA1 = has_next ? p.a_base(nxt, S1) - p.a_bias(S1) : cA1;
;         const char* nB0 = has_next ? p.b_base(nxt, 0) - p.b_bias(0) : cB0; const char* nB1 = has_next ? p.b_base(nxt, S1) - p.b_bias(S1) : cB1;
;     ...
; #pragma unroll
;         for (int a = 0; a < 2; ++a)
; #pragma unroll
;             for (int b = 0; b < 2; ++b)
; #pragma unroll
;                 for (int m = 0; m < 4; ++m)
; #pragma unroll
;                     for (int n = 0; n < 2; ++n) acc[a][b][m][n] = (f32x4){0.f, 0.f, 0.f, 0.f};
;         cur = nxt; ++ui; cA0 = nA0; cA1 = nA1; cB0 = nB0; cB1 = nB1;
.LBB0_678:
	s_ashr_i32 s53, s52, 31
	s_lshl_b64 s[18:19], s[52:53], 15
	s_add_u32 s30, s2, s18
	s_addc_u32 s31, s3, s19
	s_and_b64 s[18:19], s[48:49], exec
	s_cselect_b32 s55, s31, s61
	s_cselect_b32 s54, s30, s60
	s_lshl_b32 s18, s64, 8
	s_ashr_i32 s19, s18, 31
	s_lshl_b64 s[18:19], s[18:19], 7
	s_add_u32 s18, s24, s18
	s_addc_u32 s19, s25, s19
	s_add_u32 s56, s18, 0x40000
	s_addc_u32 s57, s19, 0
	s_and_b64 s[18:19], s[48:49], exec
	s_cselect_b32 s18, s57, s29
	s_cselect_b32 s19, s56, s28
	s_add_u32 s53, s28, 0x100000
	v_mov_b32_e32 v2, 0
	v_mov_b32_e32 v3, v2
	s_addc_u32 s59, s29, 0
	v_lshl_add_u64 v[168:169], s[60:61], 0, v[166:167]
	s_mov_b32 s66, -2
	s_mov_b64 s[62:63], 0
	v_pk_mov_b32 v[4:5], v[2:3], v[2:3]
	v_pk_mov_b32 v[6:7], v[2:3], v[2:3]
	v_pk_mov_b32 v[8:9], v[2:3], v[2:3]
	v_pk_mov_b32 v[18:19], v[2:3], v[2:3]
	v_pk_mov_b32 v[20:21], v[2:3], v[2:3]
	v_pk_mov_b32 v[22:23], v[2:3], v[2:3]
	v_pk_mov_b32 v[24:25], v[2:3], v[2:3]
	v_pk_mov_b32 v[34:35], v[2:3], v[2:3]
	v_pk_mov_b32 v[36:37], v[2:3], v[2:3]
	v_pk_mov_b32 v[38:39], v[2:3], v[2:3]
	v_pk_mov_b32 v[40:41], v[2:3], v[2:3]
	v_pk_mov_b32 v[50:51], v[2:3], v[2:3]
	v_pk_mov_b32 v[52:53], v[2:3], v[2:3]
	v_pk_mov_b32 v[54:55], v[2:3], v[2:3]
	v_pk_mov_b32 v[56:57], v[2:3], v[2:3]
	v_pk_mov_b32 v[10:11], v[2:3], v[2:3]
	v_pk_mov_b32 v[12:13], v[2:3], v[2:3]
	v_pk_mov_b32 v[14:15], v[2:3], v[2:3]
	v_pk_mov_b32 v[16:17], v[2:3], v[2:3]
	v_pk_mov_b32 v[26:27], v[2:3], v[2:3]
	v_pk_mov_b32 v[28:29], v[2:3], v[2:3]
	v_pk_mov_b32 v[30:31], v[2:3], v[2:3]
	v_pk_mov_b32 v[32:33], v[2:3], v[2:3]
	v_pk_mov_b32 v[42:43], v[2:3], v[2:3]
	v_pk_mov_b32 v[44:45], v[2:3], v[2:3]
	v_pk_mov_b32 v[46:47], v[2:3], v[2:3]
	v_pk_mov_b32 v[48:49], v[2:3], v[2:3]
	v_pk_mov_b32 v[58:59], v[2:3], v[2:3]
	v_pk_mov_b32 v[60:61], v[2:3], v[2:3]
	v_pk_mov_b32 v[62:63], v[2:3], v[2:3]
	v_pk_mov_b32 v[64:65], v[2:3], v[2:3]
	v_pk_mov_b32 v[66:67], v[2:3], v[2:3]
	v_pk_mov_b32 v[68:69], v[2:3], v[2:3]
	v_pk_mov_b32 v[70:71], v[2:3], v[2:3]
	v_pk_mov_b32 v[72:73], v[2:3], v[2:3]
	v_pk_mov_b32 v[82:83], v[2:3], v[2:3]
	v_pk_mov_b32 v[84:85], v[2:3], v[2:3]
	v_pk_mov_b32 v[86:87], v[2:3], v[2:3]
	v_pk_mov_b32 v[88:89], v[2:3], v[2:3]
	v_pk_mov_b32 v[98:99], v[2:3], v[2:3]
	v_pk_mov_b32 v[100:101], v[2:3], v[2:3]
	v_pk_mov_b32 v[102:103], v[2:3], v[2:3]
	v_pk_mov_b32 v[104:105], v[2:3], v[2:3]
	v_pk_mov_b32 v[114:115], v[2:3], v[2:3]
	v_pk_mov_b32 v[116:117], v[2:3], v[2:3]
	v_pk_mov_b32 v[118:119], v[2:3], v[2:3]
	v_pk_mov_b32 v[120:121], v[2:3], v[2:3]
	v_pk_mov_b32 v[74:75], v[2:3], v[2:3]
	v_pk_mov_b32 v[76:77], v[2:3], v[2:3]
	v_pk_mov_b32 v[78:79], v[2:3], v[2:3]
	v_pk_mov_b32 v[80:81], v[2:3], v[2:3]
	v_pk_mov_b32 v[90:91], v[2:3], v[2:3]
	v_pk_mov_b32 v[92:93], v[2:3], v[2:3]
	v_pk_mov_b32 v[94:95], v[2:3], v[2:3]
	v_pk_mov_b32 v[96:97], v[2:3], v[2:3]
	v_pk_mov_b32 v[106:107], v[2:3], v[2:3]
	v_pk_mov_b32 v[108:109], v[2:3], v[2:3]
	v_pk_mov_b32 v[110:111], v[2:3], v[2:3]
	v_pk_mov_b32 v[112:113], v[2:3], v[2:3]
	v_pk_mov_b32 v[122:123], v[2:3], v[2:3]
	v_pk_mov_b32 v[124:125], v[2:3], v[2:3]
	v_pk_mov_b32 v[126:127], v[2:3], v[2:3]
	v_pk_mov_b32 v[128:129], v[2:3], v[2:3]
	s_branch .LBB0_680

;     __host__ __device__ bool unit(int L, Unit& u) const { return order_mn(L, RT / 256, 32, u); }
;     __host__ __device__ const char* a_base(const Unit& u, int) const { return ((u.pn < 16 || u.pm >= 128) ? HX : HXV) + (size_t)u.pm * 256 * 128; }
;     __host__ __device__ bool unit(int L, Unit& u) const { if (L >= NCHB / 256) return false; u.g = g; u.pm = 0; u.pn = b * (NCHB / 256) + L; u.ks = 0; return true; }
;     __host__ __device__ bool unit(int L, Unit& u) const { constexpr int nN = TP / 256, nM = NCHB / 256; if (L >= nN * nM) return false; u.g = g; u.pm = b * nM + L / nN; u.pn = L % nN; u.ks = 0; return true; }
;     __host__ __device__ bool unit(int L, Unit& u) const { return order_mn(L, RL / 256, 8, u); }
;     __host__ __device__ bool unit(int L, Unit& u) const { return order_mn(L, RL / 256, 4, u); }
; template <class P>
; __device__ __forceinline__ void gemm_phase(LAS unsigned char* lds, const P& p, const int G, const int c) {
;     ...
;         const bool has_next = p.unit((ui + 1) * G + c, nxt);
;         const int nt = p.nt(cur);
;         const char* nA0 = has_next ? p.a_base(nxt, 0) - p.a_bias(0) : cA0; const char* nA1 = has_next ? p.a_base(nxt, S1) - p.a_bias(S1) : cA1;
;         const char* nB0 = has_next ? p.b_base(nxt, 0) - p.b_bias(0) : cB0; const char* nB1 = has_next ? p.b_base(nxt, S1) - p.b_bias(S1) : cB1;
;     ...
; #pragma unroll
;         for (int a = 0; a < 2; ++a)
; #pragma unroll
;             for (int b = 0; b < 2; ++b)
; #pragma unroll
;                 for (int m = 0; m < 4; ++m)
; #pragma unroll
;                     for (int n = 0; n < 2; ++n) acc[a][b][m][n] = (f32x4){0.f, 0.f, 0.f, 0.f};
.LBB0_706:
	s_ashr_i32 s61, s60, 31
	s_lshl_b64 s[18:19], s[60:61], 13
	s_add_u32 s68, s4, s18
	s_addc_u32 s69, s5, s19
	s_and_b64 s[18:19], s[58:59], exec
	s_cselect_b32 s18, s69, s75
	s_cselect_b32 s19, s68, s74
	s_ashr_i32 s63, s62, 31
	s_lshl_b64 s[64:65], s[62:63], 15
	s_add_u32 s70, s2, s64
	s_addc_u32 s71, s3, s65
	s_and_b64 s[64:65], s[58:59], exec
	s_cselect_b32 s61, s71, s29
	s_cselect_b32 s63, s70, s28
	s_add_u32 s28, s28, 0x80000
	v_mov_b32_e32 v2, 0
	v_mov_b32_e32 v3, v2
	s_addc_u32 s29, s29, 0
	v_lshl_add_u64 v[66:67], s[74:75], 0, v[212:213]
	s_mov_b32 s64, -2
	s_mov_b64 s[76:77], 0
	v_pk_mov_b32 v[4:5], v[2:3], v[2:3]
	v_pk_mov_b32 v[6:7], v[2:3], v[2:3]
	v_pk_mov_b32 v[8:9], v[2:3], v[2:3]
	v_pk_mov_b32 v[18:19], v[2:3], v[2:3]
	v_pk_mov_b32 v[20:21], v[2:3], v[2:3]
	v_pk_mov_b32 v[22:23], v[2:3], v[2:3]
	v_pk_mov_b32 v[24:25], v[2:3], v[2:3]
	v_pk_mov_b32 v[34:35], v[2:3], v[2:3]
	v_pk_mov_b32 v[36:37], v[2:3], v[2:3]
	v_pk_mov_b32 v[38:39], v[2:3], v[2:3]
	v_pk_mov_b32 v[40:41], v[2:3], v[2:3]
	v_pk_mov_b32 v[50:51], v[2:3], v[2:3]
	v_pk_mov_b32 v[52:53], v[2:3], v[2:3]
	v_pk_mov_b32 v[54:55], v[2:3], v[2:3]
	v_pk_mov_b32 v[56:57], v[2:3], v[2:3]
	v_pk_mov_b32 v[10:11], v[2:3], v[2:3]
	v_pk_mov_b32 v[12:13], v[2:3], v[2:3]
	v_pk_mov_b32 v[14:15], v[2:3], v[2:3]
	v_pk_mov_b32 v[16:17], v[2:3], v[2:3]
	v_pk_mov_b32 v[26:27], v[2:3], v[2:3]
	v_pk_mov_b32 v[28:29], v[2:3], v[2:3]
	v_pk_mov_b32 v[30:31], v[2:3], v[2:3]
	v_pk_mov_b32 v[32:33], v[2:3], v[2:3]
	v_pk_mov_b32 v[42:43], v[2:3], v[2:3]
	v_pk_mov_b32 v[44:45], v[2:3], v[2:3]
	v_pk_mov_b32 v[46:47], v[2:3], v[2:3]
	v_pk_mov_b32 v[48:49], v[2:3], v[2:3]
	v_pk_mov_b32 v[58:59], v[2:3], v[2:3]
	v_pk_mov_b32 v[60:61], v[2:3], v[2:3]
	v_pk_mov_b32 v[62:63], v[2:3], v[2:3]
	v_pk_mov_b32 v[64:65], v[2:3], v[2:3]
	v_pk_mov_b32 v[82:83], v[2:3], v[2:3]
	v_pk_mov_b32 v[84:85], v[2:3], v[2:3]
	v_pk_mov_b32 v[86:87], v[2:3], v[2:3]
	v_pk_mov_b32 v[88:89], v[2:3], v[2:3]
	v_pk_mov_b32 v[98:99], v[2:3], v[2:3]
	v_pk_mov_b32 v[100:101], v[2:3], v[2:3]
	v_pk_mov_b32 v[102:103], v[2:3], v[2:3]
	v_pk_mov_b32 v[104:105], v[2:3], v[2:3]
	v_pk_mov_b32 v[114:115], v[2:3], v[2:3]
	v_pk_mov_b32 v[116:117], v[2:3], v[2:3]
	v_pk_mov_b32 v[118:119], v[2:3], v[2:3]
	v_pk_mov_b32 v[120:121], v[2:3], v[2:3]
	v_pk_mov_b32 v[130:131], v[2:3], v[2:3]
	v_pk_mov_b32 v[132:133], v[2:3], v[2:3]
	v_pk_mov_b32 v[134:135], v[2:3], v[2:3]
	v_pk_mov_b32 v[136:137], v[2:3], v[2:3]
	v_pk_mov_b32 v[90:91], v[2:3], v[2:3]
	v_pk_mov_b32 v[92:93], v[2:3], v[2:3]
	v_pk_mov_b32 v[94:95], v[2:3], v[2:3]
	v_pk_mov_b32 v[96:97], v[2:3], v[2:3]
	v_pk_mov_b32 v[106:107], v[2:3], v[2:3]
	v_pk_mov_b32 v[108:109], v[2:3], v[2:3]
	v_pk_mov_b32 v[110:111], v[2:3], v[2:3]
	v_pk_mov_b32 v[112:113], v[2:3], v[2:3]
	v_pk_mov_b32 v[122:123], v[2:3], v[2:3]
	v_pk_mov_b32 v[124:125], v[2:3], v[2:3]
	v_pk_mov_b32 v[126:127], v[2:3], v[2:3]
	v_pk_mov_b32 v[128:129], v[2:3], v[2:3]
	v_pk_mov_b32 v[146:147], v[2:3], v[2:3]
	v_pk_mov_b32 v[148:149], v[2:3], v[2:3]
	v_pk_mov_b32 v[150:151], v[2:3], v[2:3]
	v_pk_mov_b32 v[152:153], v[2:3], v[2:3]

;     __host__ __device__ bool unit(int L, Unit& u) const { return order_mn(L, RT / 256, 32, u); }
;     __host__ __device__ const char* a_base(const Unit& u, int) const { return ((u.pn < 16 || u.pm >= 128) ? HX : HXV) + (size_t)u.pm * 256 * 128; }
;     __host__ __device__ bool unit(int L, Unit& u) const { if (L >= NCHB / 256) return false; u.g = g; u.pm = 0; u.pn = b * (NCHB / 256) + L; u.ks = 0; return true; }
;     __host__ __device__ bool unit(int L, Unit& u) const { constexpr int nN = TP / 256, nM = NCHB / 256; if (L >= nN * nM) return false; u.g = g; u.pm = b * nM + L / nN; u.pn = L % nN; u.ks = 0; return true; }
;     __host__ __device__ bool unit(int L, Unit& u) const { return order_mn(L, RL / 256, 8, u); }
;     __host__ __device__ bool unit(int L, Unit& u) const { return order_mn(L, RL / 256, 4, u); }
; template <class P>
; __device__ __forceinline__ void gemm_phase(LAS unsigned char* lds, const P& p, const int G, const int c) {
;     ...
;         const bool has_next = p.unit((ui + 1) * G + c, nxt);
;         const int nt = p.nt(cur);
;         const char* nA0 = has_next ? p.a_base(nxt, 0) - p.a_bias(0) : cA0; const char* nA1 = has_next ? p.a_base(nxt, S1) - p.a_bias(S1) : cA1;
;         const char* nB0 = has_next ? p.b_base(nxt, 0) - p.b_bias(0) : cB0; const char* nB1 = has_next ? p.b_base(nxt, S1) - p.b_bias(S1) : cB1;
;     ...
; #pragma unroll
;         for (int a = 0; a < 2; ++a)
; #pragma unroll
;             for (int b = 0; b < 2; ++b)
; #pragma unroll
;                 for (int m = 0; m < 4; ++m)
; #pragma unroll
;                     for (int n = 0; n < 2; ++n) acc[a][b][m][n] = (f32x4){0.f, 0.f, 0.f, 0.f};
.LBB0_769:
	s_ashr_i32 s57, s56, 31
	s_lshl_b64 s[18:19], s[56:57], 15
	s_add_u32 s60, s2, s18
	s_addc_u32 s61, s3, s19
	s_and_b64 s[18:19], s[54:55], exec
	s_cselect_b32 s18, s61, s71
	s_cselect_b32 s19, s60, s70
	s_ashr_i32 s59, s58, 31
	s_lshl_b64 s[62:63], s[58:59], 15
	s_add_u32 s62, s24, s62
	s_addc_u32 s63, s25, s63
	s_and_b64 s[72:73], s[54:55], exec
	s_cselect_b32 s57, s63, s29
	s_cselect_b32 s59, s62, s28
	s_add_u32 s28, s28, 0x40000
	v_mov_b32_e32 v0, 0
	v_mov_b32_e32 v1, v0
	s_addc_u32 s29, s29, 0
	v_lshl_add_u64 v[128:129], s[70:71], 0, v[152:153]
	s_mov_b32 s76, -2
	s_mov_b64 s[72:73], 0
	v_pk_mov_b32 v[2:3], v[0:1], v[0:1]
	v_pk_mov_b32 v[4:5], v[0:1], v[0:1]
	v_pk_mov_b32 v[6:7], v[0:1], v[0:1]
	v_pk_mov_b32 v[8:9], v[0:1], v[0:1]
	v_pk_mov_b32 v[10:11], v[0:1], v[0:1]
	v_pk_mov_b32 v[16:17], v[0:1], v[0:1]
	v_pk_mov_b32 v[18:19], v[0:1], v[0:1]
	v_pk_mov_b32 v[24:25], v[0:1], v[0:1]
	v_pk_mov_b32 v[26:27], v[0:1], v[0:1]
	v_pk_mov_b32 v[32:33], v[0:1], v[0:1]
	v_pk_mov_b32 v[34:35], v[0:1], v[0:1]
	v_pk_mov_b32 v[40:41], v[0:1], v[0:1]
	v_pk_mov_b32 v[42:43], v[0:1], v[0:1]
	v_pk_mov_b32 v[48:49], v[0:1], v[0:1]
	v_pk_mov_b32 v[50:51], v[0:1], v[0:1]
	v_pk_mov_b32 v[12:13], v[0:1], v[0:1]
	v_pk_mov_b32 v[14:15], v[0:1], v[0:1]
	v_pk_mov_b32 v[20:21], v[0:1], v[0:1]
	v_pk_mov_b32 v[22:23], v[0:1], v[0:1]
	v_pk_mov_b32 v[28:29], v[0:1], v[0:1]
	v_pk_mov_b32 v[30:31], v[0:1], v[0:1]
	v_pk_mov_b32 v[36:37], v[0:1], v[0:1]
	v_pk_mov_b32 v[38:39], v[0:1], v[0:1]
	v_pk_mov_b32 v[44:45], v[0:1], v[0:1]
	v_pk_mov_b32 v[46:47], v[0:1], v[0:1]
	v_pk_mov_b32 v[52:53], v[0:1], v[0:1]
	v_pk_mov_b32 v[54:55], v[0:1], v[0:1]
	v_pk_mov_b32 v[56:57], v[0:1], v[0:1]
	v_pk_mov_b32 v[58:59], v[0:1], v[0:1]
	v_pk_mov_b32 v[60:61], v[0:1], v[0:1]
	v_pk_mov_b32 v[62:63], v[0:1], v[0:1]
	v_pk_mov_b32 v[64:65], v[0:1], v[0:1]
	v_pk_mov_b32 v[66:67], v[0:1], v[0:1]
	v_pk_mov_b32 v[68:69], v[0:1], v[0:1]
	v_pk_mov_b32 v[70:71], v[0:1], v[0:1]
	v_pk_mov_b32 v[76:77], v[0:1], v[0:1]
	v_pk_mov_b32 v[78:79], v[0:1], v[0:1]
	v_pk_mov_b32 v[88:89], v[0:1], v[0:1]
	v_pk_mov_b32 v[90:91], v[0:1], v[0:1]
	v_pk_mov_b32 v[80:81], v[0:1], v[0:1]
	v_pk_mov_b32 v[82:83], v[0:1], v[0:1]
	v_pk_mov_b32 v[96:97], v[0:1], v[0:1]
	v_pk_mov_b32 v[98:99], v[0:1], v[0:1]
	v_pk_mov_b32 v[92:93], v[0:1], v[0:1]
	v_pk_mov_b32 v[94:95], v[0:1], v[0:1]
	v_pk_mov_b32 v[104:105], v[0:1], v[0:1]
	v_pk_mov_b32 v[106:107], v[0:1], v[0:1]
	v_pk_mov_b32 v[72:73], v[0:1], v[0:1]
	v_pk_mov_b32 v[74:75], v[0:1], v[0:1]
	v_pk_mov_b32 v[84:85], v[0:1], v[0:1]
	v_pk_mov_b32 v[86:87], v[0:1], v[0:1]
	v_pk_mov_b32 v[108:109], v[0:1], v[0:1]
	v_pk_mov_b32 v[110:111], v[0:1], v[0:1]
	v_pk_mov_b32 v[100:101], v[0:1], v[0:1]
	v_pk_mov_b32 v[102:103], v[0:1], v[0:1]
	v_pk_mov_b32 v[116:117], v[0:1], v[0:1]
	v_pk_mov_b32 v[118:119], v[0:1], v[0:1]
	v_pk_mov_b32 v[112:113], v[0:1], v[0:1]
	v_pk_mov_b32 v[114:115], v[0:1], v[0:1]
	v_pk_mov_b32 v[124:125], v[0:1], v[0:1]
	v_pk_mov_b32 v[126:127], v[0:1], v[0:1]
	v_pk_mov_b32 v[120:121], v[0:1], v[0:1]
	v_pk_mov_b32 v[122:123], v[0:1], v[0:1]
